# speedup vs baseline: 1.1233x; 1.0005x over previous
;     ...
;     if constexpr (EPI == EPI_RESID) {
;       const int cv = brow < MLAT ? (brow >> 11) : 8;
;       const float* gate = fa + cv * 9216;
;       float* Xp = (float*)(ws + OFF_X);
; #pragma unroll
;       for (int n = 0; n < 4; ++n) {
;         const int col0 = bcol + wc * 64 + n * 16 + fq * 4;
;         float4 g4 = *(const float4*)(gate + col0);
;         g4.x *= cs; g4.y *= cs; g4.z *= cs; g4.w *= cs;
;         float4 b4 = float4{0.f, 0.f, 0.f, 0.f};
;         if (fb) b4 = *(const float4*)(fb + col0);
; #pragma unroll
;         for (int m = 0; m < MT; ++m) {
;           if (sp == 1) {
;             float4 pv;
;             pv.x = g4.x * acc[m][n][0]; pv.y = g4.y * acc[m][n][1]; pv.z = g4.z * acc[m][n][2]; pv.w = g4.w * acc[m][n][3];
;             *(float4*)((float*)(ws + OFF_PART) + (size_t)(rbase + m * 16 - MLAT) * DM + col0) = pv;
;             continue;
;           }
;           float4* px = (float4*)(Xp + (size_t)(rbase + m * 16) * DM + col0);
;           float4 x = *px;
;           x.x = alpha * x.x + g4.x * (acc[m][n][0] + b4.x);
;           x.y = alpha * x.y + g4.y * (acc[m][n][1] + b4.y);
;           x.z = alpha * x.z + g4.z * (acc[m][n][2] + b4.z);
;           x.w = alpha * x.w + g4.w * (acc[m][n][3] + b4.w);
;           *px = x;
;         }
;       }
.LBB0_1054:
	s_andn2_b64 vcc, exec, s[16:17]
	s_mov_b32 s24, s23
	s_mov_b32 s25, s22
	s_mov_b64 s[0:1], s[12:13]
	s_mov_b64 s[18:19], s[14:15]
	s_cbranch_vccz .LBB0_1071

;     ...
;     const int rbase = brow + wr * (BM / 2) + fr;
;     if constexpr (EPI == EPI_RESID) {
;       const int cv = brow < MLAT ? (brow >> 11) : 8;
;       const float* gate = fa + cv * 9216;
;       float* Xp = (float*)(ws + OFF_X);
; #pragma unroll
;       for (int n = 0; n < 4; ++n) {
;         const int col0 = bcol + wc * 64 + n * 16 + fq * 4;
;         float4 g4 = *(const float4*)(gate + col0);
;         g4.x *= cs; g4.y *= cs; g4.z *= cs; g4.w *= cs;
;         float4 b4 = float4{0.f, 0.f, 0.f, 0.f};
;         if (fb) b4 = *(const float4*)(fb + col0);
; #pragma unroll
;         for (int m = 0; m < MT; ++m) {
;           if (sp == 1) {
;             float4 pv;
;             pv.x = g4.x * acc[m][n][0]; pv.y = g4.y * acc[m][n][1]; pv.z = g4.z * acc[m][n][2]; pv.w = g4.w * acc[m][n][3];
;             *(float4*)((float*)(ws + OFF_PART) + (size_t)(rbase + m * 16 - MLAT) * DM + col0) = pv;
;             continue;
;           }
;           float4* px = (float4*)(Xp + (size_t)(rbase + m * 16) * DM + col0);
;           float4 x = *px;
;           x.x = alpha * x.x + g4.x * (acc[m][n][0] + b4.x);
;           x.y = alpha * x.y + g4.y * (acc[m][n][1] + b4.y);
;           x.z = alpha * x.z + g4.z * (acc[m][n][2] + b4.z);
;           x.w = alpha * x.w + g4.w * (acc[m][n][3] + b4.w);
;           *px = x;
;         }
;       }
.LBB0_1063:
	v_mfma_f32_16x16x32_bf16 v[100:103], v[88:91], v[32:35], v[64:67]
	v_mfma_f32_16x16x32_bf16 v[64:67], v[92:95], v[32:35], v[124:127]
	v_mfma_f32_16x16x32_bf16 v[32:35], v[132:135], v[32:35], v[136:139]
	v_mfma_f32_16x16x32_bf16 v[124:127], v[56:59], v[176:179], v[164:167]
	v_mfma_f32_16x16x32_bf16 v[88:91], v[88:91], v[176:179], v[168:171]
	v_mfma_f32_16x16x32_bf16 v[56:59], v[92:95], v[176:179], v[172:175]
	v_mfma_f32_16x16x32_bf16 v[24:27], v[132:135], v[176:179], v[24:27]
	s_lshr_b32 s0, s24, 3
	s_mulk_i32 s0, 0x2400
	s_ashr_i32 s1, s0, 31
	s_lshl_b64 s[0:1], s[0:1], 2
	s_add_u32 s0, s89, s0
	s_addc_u32 s1, s94, s1
	v_lshl_add_u32 v200, s24, 8, v245
	v_lshl_or_b32 v192, s25, 8, v244
	v_ashrrev_i32_e32 v193, 31, v192
	v_lshlrev_b64 v[194:195], 2, v[192:193]
	v_lshl_add_u64 v[196:197], s[0:1], 0, v[194:195]
	v_lshl_add_u64 v[198:199], s[8:9], 0, v[194:195]
	v_lshlrev_b32_e32 v201, 12, v200
	v_add_u32_e32 v201, v201, v194
	global_load_dwordx4 v[92:95], v[196:197], off
	global_load_dwordx4 v[132:135], v[196:197], off offset:64
	global_load_dwordx4 v[136:139], v[196:197], off offset:128
	global_load_dwordx4 v[164:167], v[196:197], off offset:192
	v_mov_b32_e32 v168, 0
	v_mov_b32_e32 v169, 0
	v_mov_b32_e32 v170, 0
	v_mov_b32_e32 v171, 0
	v_mov_b32_e32 v172, 0
	v_mov_b32_e32 v173, 0
	v_mov_b32_e32 v174, 0
	v_mov_b32_e32 v175, 0
	v_mov_b32_e32 v176, 0
	v_mov_b32_e32 v177, 0
	v_mov_b32_e32 v178, 0
	v_mov_b32_e32 v179, 0
	v_mov_b32_e32 v180, 0
	v_mov_b32_e32 v181, 0
	v_mov_b32_e32 v182, 0
	v_mov_b32_e32 v183, 0
	s_and_b64 vcc, exec, s[6:7]
	s_cbranch_vccz .Lmy_out256_nobias
	global_load_dwordx4 v[168:171], v[198:199], off
	global_load_dwordx4 v[172:175], v[198:199], off offset:64
	global_load_dwordx4 v[176:179], v[198:199], off offset:128
	global_load_dwordx4 v[180:183], v[198:199], off offset:192
.Lmy_out256_nobias:
	s_waitcnt vmcnt(0)
	v_pk_add_f32 v[160:161], v[160:161], v[168:169]
	v_pk_add_f32 v[162:163], v[162:163], v[170:171]
	v_pk_add_f32 v[156:157], v[156:157], v[168:169]
	v_pk_add_f32 v[158:159], v[158:159], v[170:171]
	v_pk_add_f32 v[152:153], v[152:153], v[168:169]
	v_pk_add_f32 v[154:155], v[154:155], v[170:171]
	v_pk_add_f32 v[148:149], v[148:149], v[168:169]
	v_pk_add_f32 v[150:151], v[150:151], v[170:171]
	v_pk_add_f32 v[144:145], v[144:145], v[168:169]
	v_pk_add_f32 v[146:147], v[146:147], v[170:171]
	v_pk_add_f32 v[140:141], v[140:141], v[168:169]
	v_pk_add_f32 v[142:143], v[142:143], v[170:171]
	v_pk_add_f32 v[128:129], v[128:129], v[168:169]
	v_pk_add_f32 v[130:131], v[130:131], v[170:171]
	v_pk_add_f32 v[124:125], v[124:125], v[168:169]
	v_pk_add_f32 v[126:127], v[126:127], v[170:171]
	v_pk_add_f32 v[120:121], v[120:121], v[172:173]
	v_pk_add_f32 v[122:123], v[122:123], v[174:175]
	v_pk_add_f32 v[116:117], v[116:117], v[172:173]
	v_pk_add_f32 v[118:119], v[118:119], v[174:175]
	v_pk_add_f32 v[112:113], v[112:113], v[172:173]
	v_pk_add_f32 v[114:115], v[114:115], v[174:175]
	v_pk_add_f32 v[108:109], v[108:109], v[172:173]
	v_pk_add_f32 v[110:111], v[110:111], v[174:175]
	v_pk_add_f32 v[104:105], v[104:105], v[172:173]
	v_pk_add_f32 v[106:107], v[106:107], v[174:175]
	v_pk_add_f32 v[96:97], v[96:97], v[172:173]
	v_pk_add_f32 v[98:99], v[98:99], v[174:175]
	v_pk_add_f32 v[100:101], v[100:101], v[172:173]
	v_pk_add_f32 v[102:103], v[102:103], v[174:175]
	v_pk_add_f32 v[88:89], v[88:89], v[172:173]
	v_pk_add_f32 v[90:91], v[90:91], v[174:175]
	v_pk_add_f32 v[84:85], v[84:85], v[176:177]
	v_pk_add_f32 v[86:87], v[86:87], v[178:179]
	v_pk_add_f32 v[80:81], v[80:81], v[176:177]
	v_pk_add_f32 v[82:83], v[82:83], v[178:179]
	v_pk_add_f32 v[76:77], v[76:77], v[176:177]
	v_pk_add_f32 v[78:79], v[78:79], v[178:179]
	v_pk_add_f32 v[72:73], v[72:73], v[176:177]
	v_pk_add_f32 v[74:75], v[74:75], v[178:179]
	v_pk_add_f32 v[68:69], v[68:69], v[176:177]
	v_pk_add_f32 v[70:71], v[70:71], v[178:179]
	v_pk_add_f32 v[60:61], v[60:61], v[176:177]
	v_pk_add_f32 v[62:63], v[62:63], v[178:179]
	v_pk_add_f32 v[64:65], v[64:65], v[176:177]
	v_pk_add_f32 v[66:67], v[66:67], v[178:179]
	v_pk_add_f32 v[56:57], v[56:57], v[176:177]
	v_pk_add_f32 v[58:59], v[58:59], v[178:179]
	v_pk_add_f32 v[52:53], v[52:53], v[180:181]
	v_pk_add_f32 v[54:55], v[54:55], v[182:183]
	v_pk_add_f32 v[48:49], v[48:49], v[180:181]
	v_pk_add_f32 v[50:51], v[50:51], v[182:183]
	v_pk_add_f32 v[44:45], v[44:45], v[180:181]
	v_pk_add_f32 v[46:47], v[46:47], v[182:183]
	v_pk_add_f32 v[40:41], v[40:41], v[180:181]
	v_pk_add_f32 v[42:43], v[42:43], v[182:183]
	v_pk_add_f32 v[36:37], v[36:37], v[180:181]
	v_pk_add_f32 v[38:39], v[38:39], v[182:183]
	v_pk_add_f32 v[28:29], v[28:29], v[180:181]
	v_pk_add_f32 v[30:31], v[30:31], v[182:183]
	v_pk_add_f32 v[32:33], v[32:33], v[180:181]
	v_pk_add_f32 v[34:35], v[34:35], v[182:183]
	v_pk_add_f32 v[24:25], v[24:25], v[180:181]
	v_pk_add_f32 v[26:27], v[26:27], v[182:183]
	s_add_u32 s98, s36, 0x0
	s_addc_u32 s99, s37, 0
	global_load_dwordx4 v[168:171], v201, s[98:99]
	s_add_u32 s98, s36, 0x0
	s_addc_u32 s99, s37, 0
	global_load_dwordx4 v[172:175], v201, s[98:99] offset:64
	s_add_u32 s98, s36, 0x0
	s_addc_u32 s99, s37, 0
	global_load_dwordx4 v[176:179], v201, s[98:99] offset:128
	s_add_u32 s98, s36, 0x0
	s_addc_u32 s99, s37, 0
	global_load_dwordx4 v[180:183], v201, s[98:99] offset:192
	s_add_u32 s98, s36, 0x10000
	s_addc_u32 s99, s37, 0
	global_load_dwordx4 v[184:187], v201, s[98:99]
	s_add_u32 s98, s36, 0x10000
	s_addc_u32 s99, s37, 0
	global_load_dwordx4 v[188:191], v201, s[98:99] offset:64
	s_waitcnt vmcnt(5)
;     ...
;           float4* px = (float4*)(Xp + (size_t)(rbase + m * 16) * DM + col0);
;           float4 x = *px;
;           x.x = alpha * x.x + g4.x * (acc[m][n][0] + b4.x);
;           x.y = alpha * x.y + g4.y * (acc[m][n][1] + b4.y);
;           x.z = alpha * x.z + g4.z * (acc[m][n][2] + b4.z);
;           x.w = alpha * x.w + g4.w * (acc[m][n][3] + b4.w);
;           *px = x;
;         }
	v_pk_mul_f32 v[168:169], v[168:169], s[52:53] op_sel_hi:[1,0]
	v_pk_mul_f32 v[170:171], v[170:171], s[52:53] op_sel_hi:[1,0]
	v_pk_fma_f32 v[160:161], v[92:93], v[160:161], v[168:169]
	v_pk_fma_f32 v[162:163], v[94:95], v[162:163], v[170:171]
	s_add_u32 s100, s36, 0x0
	s_addc_u32 s101, s37, 0
	global_store_dwordx4 v201, v[160:163], s[100:101]
	s_add_u32 s98, s36, 0x10000
	s_addc_u32 s99, s37, 0
	global_load_dwordx4 v[168:171], v201, s[98:99] offset:128
	s_waitcnt vmcnt(6)
	v_pk_mul_f32 v[172:173], v[172:173], s[52:53] op_sel_hi:[1,0]
	v_pk_mul_f32 v[174:175], v[174:175], s[52:53] op_sel_hi:[1,0]
	v_pk_fma_f32 v[120:121], v[132:133], v[120:121], v[172:173]
	v_pk_fma_f32 v[122:123], v[134:135], v[122:123], v[174:175]
	s_add_u32 s100, s36, 0x0
	s_addc_u32 s101, s37, 0
	global_store_dwordx4 v201, v[120:123], s[100:101] offset:64
	s_add_u32 s98, s36, 0x10000
	s_addc_u32 s99, s37, 0
	global_load_dwordx4 v[172:175], v201, s[98:99] offset:192
	s_waitcnt vmcnt(7)
	v_pk_mul_f32 v[176:177], v[176:177], s[52:53] op_sel_hi:[1,0]
	v_pk_mul_f32 v[178:179], v[178:179], s[52:53] op_sel_hi:[1,0]
	v_pk_fma_f32 v[84:85], v[136:137], v[84:85], v[176:177]
	v_pk_fma_f32 v[86:87], v[138:139], v[86:87], v[178:179]
	s_add_u32 s100, s36, 0x0
	s_addc_u32 s101, s37, 0
	global_store_dwordx4 v201, v[84:87], s[100:101] offset:128
	s_add_u32 s98, s36, 0x20000
	s_addc_u32 s99, s37, 0
	global_load_dwordx4 v[176:179], v201, s[98:99]
	s_waitcnt vmcnt(8)
	v_pk_mul_f32 v[180:181], v[180:181], s[52:53] op_sel_hi:[1,0]
	v_pk_mul_f32 v[182:183], v[182:183], s[52:53] op_sel_hi:[1,0]
	v_pk_fma_f32 v[52:53], v[164:165], v[52:53], v[180:181]
	v_pk_fma_f32 v[54:55], v[166:167], v[54:55], v[182:183]
	s_add_u32 s100, s36, 0x0
	s_addc_u32 s101, s37, 0
	global_store_dwordx4 v201, v[52:55], s[100:101] offset:192
	s_add_u32 s98, s36, 0x20000
	s_addc_u32 s99, s37, 0
	global_load_dwordx4 v[180:183], v201, s[98:99] offset:64
	s_waitcnt vmcnt(9)
	v_pk_mul_f32 v[184:185], v[184:185], s[52:53] op_sel_hi:[1,0]
	v_pk_mul_f32 v[186:187], v[186:187], s[52:53] op_sel_hi:[1,0]
	v_pk_fma_f32 v[156:157], v[92:93], v[156:157], v[184:185]
	v_pk_fma_f32 v[158:159], v[94:95], v[158:159], v[186:187]
	s_add_u32 s100, s36, 0x10000
	s_addc_u32 s101, s37, 0
	global_store_dwordx4 v201, v[156:159], s[100:101]
	s_add_u32 s98, s36, 0x20000
	s_addc_u32 s99, s37, 0
	global_load_dwordx4 v[184:187], v201, s[98:99] offset:128
	s_waitcnt vmcnt(10)
	v_pk_mul_f32 v[188:189], v[188:189], s[52:53] op_sel_hi:[1,0]
	v_pk_mul_f32 v[190:191], v[190:191], s[52:53] op_sel_hi:[1,0]
	v_pk_fma_f32 v[116:117], v[132:133], v[116:117], v[188:189]
	v_pk_fma_f32 v[118:119], v[134:135], v[118:119], v[190:191]
	s_add_u32 s100, s36, 0x10000
	s_addc_u32 s101, s37, 0
	global_store_dwordx4 v201, v[116:119], s[100:101] offset:64
	s_add_u32 s98, s36, 0x20000
	s_addc_u32 s99, s37, 0
	global_load_dwordx4 v[188:191], v201, s[98:99] offset:192
	s_waitcnt vmcnt(10)
	v_pk_mul_f32 v[168:169], v[168:169], s[52:53] op_sel_hi:[1,0]
	v_pk_mul_f32 v[170:171], v[170:171], s[52:53] op_sel_hi:[1,0]
	v_pk_fma_f32 v[80:81], v[136:137], v[80:81], v[168:169]
	v_pk_fma_f32 v[82:83], v[138:139], v[82:83], v[170:171]
	s_add_u32 s100, s36, 0x10000
	s_addc_u32 s101, s37, 0
	global_store_dwordx4 v201, v[80:83], s[100:101] offset:128
	s_add_u32 s98, s36, 0x30000
	s_addc_u32 s99, s37, 0
	global_load_dwordx4 v[168:171], v201, s[98:99]
	s_waitcnt vmcnt(10)
	v_pk_mul_f32 v[172:173], v[172:173], s[52:53] op_sel_hi:[1,0]
	v_pk_mul_f32 v[174:175], v[174:175], s[52:53] op_sel_hi:[1,0]
	v_pk_fma_f32 v[48:49], v[164:165], v[48:49], v[172:173]
	v_pk_fma_f32 v[50:51], v[166:167], v[50:51], v[174:175]
	s_add_u32 s100, s36, 0x10000
	s_addc_u32 s101, s37, 0
	global_store_dwordx4 v201, v[48:51], s[100:101] offset:192
	s_add_u32 s98, s36, 0x30000
	s_addc_u32 s99, s37, 0
	global_load_dwordx4 v[172:175], v201, s[98:99] offset:64
	s_waitcnt vmcnt(10)
	v_pk_mul_f32 v[176:177], v[176:177], s[52:53] op_sel_hi:[1,0]
	v_pk_mul_f32 v[178:179], v[178:179], s[52:53] op_sel_hi:[1,0]
	v_pk_fma_f32 v[152:153], v[92:93], v[152:153], v[176:177]
	v_pk_fma_f32 v[154:155], v[94:95], v[154:155], v[178:179]
	s_add_u32 s100, s36, 0x20000
	s_addc_u32 s101, s37, 0
	global_store_dwordx4 v201, v[152:155], s[100:101]
	s_add_u32 s98, s36, 0x30000
	s_addc_u32 s99, s37, 0
	global_load_dwordx4 v[176:179], v201, s[98:99] offset:128
	s_waitcnt vmcnt(10)
	v_pk_mul_f32 v[180:181], v[180:181], s[52:53] op_sel_hi:[1,0]
	v_pk_mul_f32 v[182:183], v[182:183], s[52:53] op_sel_hi:[1,0]
	v_pk_fma_f32 v[112:113], v[132:133], v[112:113], v[180:181]
	v_pk_fma_f32 v[114:115], v[134:135], v[114:115], v[182:183]
	s_add_u32 s100, s36, 0x20000
	s_addc_u32 s101, s37, 0
	global_store_dwordx4 v201, v[112:115], s[100:101] offset:64
	s_add_u32 s98, s36, 0x30000
	s_addc_u32 s99, s37, 0
	global_load_dwordx4 v[180:183], v201, s[98:99] offset:192
	s_waitcnt vmcnt(10)
	v_pk_mul_f32 v[184:185], v[184:185], s[52:53] op_sel_hi:[1,0]
	v_pk_mul_f32 v[186:187], v[186:187], s[52:53] op_sel_hi:[1,0]
	v_pk_fma_f32 v[76:77], v[136:137], v[76:77], v[184:185]
	v_pk_fma_f32 v[78:79], v[138:139], v[78:79], v[186:187]
	s_add_u32 s100, s36, 0x20000
	s_addc_u32 s101, s37, 0
	global_store_dwordx4 v201, v[76:79], s[100:101] offset:128
	s_add_u32 s98, s36, 0x40000
	s_addc_u32 s99, s37, 0
	global_load_dwordx4 v[184:187], v201, s[98:99]
	s_waitcnt vmcnt(10)
	v_pk_mul_f32 v[188:189], v[188:189], s[52:53] op_sel_hi:[1,0]
	v_pk_mul_f32 v[190:191], v[190:191], s[52:53] op_sel_hi:[1,0]
	v_pk_fma_f32 v[44:45], v[164:165], v[44:45], v[188:189]
	v_pk_fma_f32 v[46:47], v[166:167], v[46:47], v[190:191]
	s_add_u32 s100, s36, 0x20000
	s_addc_u32 s101, s37, 0
	global_store_dwordx4 v201, v[44:47], s[100:101] offset:192
	s_add_u32 s98, s36, 0x40000
	s_addc_u32 s99, s37, 0
	global_load_dwordx4 v[188:191], v201, s[98:99] offset:64
	s_waitcnt vmcnt(10)
;     ...
;           float4* px = (float4*)(Xp + (size_t)(rbase + m * 16) * DM + col0);
;           float4 x = *px;
;           x.x = alpha * x.x + g4.x * (acc[m][n][0] + b4.x);
;           x.y = alpha * x.y + g4.y * (acc[m][n][1] + b4.y);
;           x.z = alpha * x.z + g4.z * (acc[m][n][2] + b4.z);
;           x.w = alpha * x.w + g4.w * (acc[m][n][3] + b4.w);
;           *px = x;
;         }
	v_pk_mul_f32 v[168:169], v[168:169], s[52:53] op_sel_hi:[1,0]
	v_pk_mul_f32 v[170:171], v[170:171], s[52:53] op_sel_hi:[1,0]
	v_pk_fma_f32 v[148:149], v[92:93], v[148:149], v[168:169]
	v_pk_fma_f32 v[150:151], v[94:95], v[150:151], v[170:171]
	s_add_u32 s100, s36, 0x30000
	s_addc_u32 s101, s37, 0
	global_store_dwordx4 v201, v[148:151], s[100:101]
	s_add_u32 s98, s36, 0x40000
	s_addc_u32 s99, s37, 0
	global_load_dwordx4 v[168:171], v201, s[98:99] offset:128
	s_waitcnt vmcnt(10)
	v_pk_mul_f32 v[172:173], v[172:173], s[52:53] op_sel_hi:[1,0]
	v_pk_mul_f32 v[174:175], v[174:175], s[52:53] op_sel_hi:[1,0]
	v_pk_fma_f32 v[108:109], v[132:133], v[108:109], v[172:173]
	v_pk_fma_f32 v[110:111], v[134:135], v[110:111], v[174:175]
	s_add_u32 s100, s36, 0x30000
	s_addc_u32 s101, s37, 0
	global_store_dwordx4 v201, v[108:111], s[100:101] offset:64
	s_add_u32 s98, s36, 0x40000
	s_addc_u32 s99, s37, 0
	global_load_dwordx4 v[172:175], v201, s[98:99] offset:192
	s_waitcnt vmcnt(10)
	v_pk_mul_f32 v[176:177], v[176:177], s[52:53] op_sel_hi:[1,0]
	v_pk_mul_f32 v[178:179], v[178:179], s[52:53] op_sel_hi:[1,0]
	v_pk_fma_f32 v[72:73], v[136:137], v[72:73], v[176:177]
	v_pk_fma_f32 v[74:75], v[138:139], v[74:75], v[178:179]
	s_add_u32 s100, s36, 0x30000
	s_addc_u32 s101, s37, 0
	global_store_dwordx4 v201, v[72:75], s[100:101] offset:128
	s_add_u32 s98, s36, 0x50000
	s_addc_u32 s99, s37, 0
	global_load_dwordx4 v[176:179], v201, s[98:99]
	s_waitcnt vmcnt(10)
	v_pk_mul_f32 v[180:181], v[180:181], s[52:53] op_sel_hi:[1,0]
	v_pk_mul_f32 v[182:183], v[182:183], s[52:53] op_sel_hi:[1,0]
	v_pk_fma_f32 v[40:41], v[164:165], v[40:41], v[180:181]
	v_pk_fma_f32 v[42:43], v[166:167], v[42:43], v[182:183]
	s_add_u32 s100, s36, 0x30000
	s_addc_u32 s101, s37, 0
	global_store_dwordx4 v201, v[40:43], s[100:101] offset:192
	s_add_u32 s98, s36, 0x50000
	s_addc_u32 s99, s37, 0
	global_load_dwordx4 v[180:183], v201, s[98:99] offset:64
	s_waitcnt vmcnt(10)
	v_pk_mul_f32 v[184:185], v[184:185], s[52:53] op_sel_hi:[1,0]
	v_pk_mul_f32 v[186:187], v[186:187], s[52:53] op_sel_hi:[1,0]
	v_pk_fma_f32 v[144:145], v[92:93], v[144:145], v[184:185]
	v_pk_fma_f32 v[146:147], v[94:95], v[146:147], v[186:187]
	s_add_u32 s100, s36, 0x40000
	s_addc_u32 s101, s37, 0
	global_store_dwordx4 v201, v[144:147], s[100:101]
	s_add_u32 s98, s36, 0x50000
	s_addc_u32 s99, s37, 0
	global_load_dwordx4 v[184:187], v201, s[98:99] offset:128
	s_waitcnt vmcnt(10)
	v_pk_mul_f32 v[188:189], v[188:189], s[52:53] op_sel_hi:[1,0]
	v_pk_mul_f32 v[190:191], v[190:191], s[52:53] op_sel_hi:[1,0]
	v_pk_fma_f32 v[104:105], v[132:133], v[104:105], v[188:189]
	v_pk_fma_f32 v[106:107], v[134:135], v[106:107], v[190:191]
	s_add_u32 s100, s36, 0x40000
	s_addc_u32 s101, s37, 0
	global_store_dwordx4 v201, v[104:107], s[100:101] offset:64
	s_add_u32 s98, s36, 0x50000
	s_addc_u32 s99, s37, 0
	global_load_dwordx4 v[188:191], v201, s[98:99] offset:192
	s_waitcnt vmcnt(10)
	v_pk_mul_f32 v[168:169], v[168:169], s[52:53] op_sel_hi:[1,0]
	v_pk_mul_f32 v[170:171], v[170:171], s[52:53] op_sel_hi:[1,0]
	v_pk_fma_f32 v[68:69], v[136:137], v[68:69], v[168:169]
	v_pk_fma_f32 v[70:71], v[138:139], v[70:71], v[170:171]
	s_add_u32 s100, s36, 0x40000
	s_addc_u32 s101, s37, 0
	global_store_dwordx4 v201, v[68:71], s[100:101] offset:128
	s_add_u32 s98, s36, 0x60000
	s_addc_u32 s99, s37, 0
	global_load_dwordx4 v[168:171], v201, s[98:99]
	s_waitcnt vmcnt(10)
	v_pk_mul_f32 v[172:173], v[172:173], s[52:53] op_sel_hi:[1,0]
	v_pk_mul_f32 v[174:175], v[174:175], s[52:53] op_sel_hi:[1,0]
	v_pk_fma_f32 v[36:37], v[164:165], v[36:37], v[172:173]
	v_pk_fma_f32 v[38:39], v[166:167], v[38:39], v[174:175]
	s_add_u32 s100, s36, 0x40000
	s_addc_u32 s101, s37, 0
	global_store_dwordx4 v201, v[36:39], s[100:101] offset:192
	s_add_u32 s98, s36, 0x60000
	s_addc_u32 s99, s37, 0
	global_load_dwordx4 v[172:175], v201, s[98:99] offset:64
	s_waitcnt vmcnt(10)
	v_pk_mul_f32 v[176:177], v[176:177], s[52:53] op_sel_hi:[1,0]
	v_pk_mul_f32 v[178:179], v[178:179], s[52:53] op_sel_hi:[1,0]
	v_pk_fma_f32 v[140:141], v[92:93], v[140:141], v[176:177]
	v_pk_fma_f32 v[142:143], v[94:95], v[142:143], v[178:179]
	s_add_u32 s100, s36, 0x50000
	s_addc_u32 s101, s37, 0
	global_store_dwordx4 v201, v[140:143], s[100:101]
	s_add_u32 s98, s36, 0x60000
	s_addc_u32 s99, s37, 0
	global_load_dwordx4 v[176:179], v201, s[98:99] offset:128
	s_waitcnt vmcnt(10)
;     ...
;           float4* px = (float4*)(Xp + (size_t)(rbase + m * 16) * DM + col0);
;           float4 x = *px;
;           x.x = alpha * x.x + g4.x * (acc[m][n][0] + b4.x);
;           x.y = alpha * x.y + g4.y * (acc[m][n][1] + b4.y);
;           x.z = alpha * x.z + g4.z * (acc[m][n][2] + b4.z);
;           x.w = alpha * x.w + g4.w * (acc[m][n][3] + b4.w);
;           *px = x;
;         }
	v_pk_mul_f32 v[180:181], v[180:181], s[52:53] op_sel_hi:[1,0]
	v_pk_mul_f32 v[182:183], v[182:183], s[52:53] op_sel_hi:[1,0]
	v_pk_fma_f32 v[96:97], v[132:133], v[96:97], v[180:181]
	v_pk_fma_f32 v[98:99], v[134:135], v[98:99], v[182:183]
	s_add_u32 s100, s36, 0x50000
	s_addc_u32 s101, s37, 0
	global_store_dwordx4 v201, v[96:99], s[100:101] offset:64
	s_add_u32 s98, s36, 0x60000
	s_addc_u32 s99, s37, 0
	global_load_dwordx4 v[180:183], v201, s[98:99] offset:192
	s_waitcnt vmcnt(10)
	v_pk_mul_f32 v[184:185], v[184:185], s[52:53] op_sel_hi:[1,0]
	v_pk_mul_f32 v[186:187], v[186:187], s[52:53] op_sel_hi:[1,0]
	v_pk_fma_f32 v[60:61], v[136:137], v[60:61], v[184:185]
	v_pk_fma_f32 v[62:63], v[138:139], v[62:63], v[186:187]
	s_add_u32 s100, s36, 0x50000
	s_addc_u32 s101, s37, 0
	global_store_dwordx4 v201, v[60:63], s[100:101] offset:128
	s_add_u32 s98, s36, 0x70000
	s_addc_u32 s99, s37, 0
	global_load_dwordx4 v[184:187], v201, s[98:99]
	s_waitcnt vmcnt(10)
	v_pk_mul_f32 v[188:189], v[188:189], s[52:53] op_sel_hi:[1,0]
	v_pk_mul_f32 v[190:191], v[190:191], s[52:53] op_sel_hi:[1,0]
	v_pk_fma_f32 v[28:29], v[164:165], v[28:29], v[188:189]
	v_pk_fma_f32 v[30:31], v[166:167], v[30:31], v[190:191]
	s_add_u32 s100, s36, 0x50000
	s_addc_u32 s101, s37, 0
	global_store_dwordx4 v201, v[28:31], s[100:101] offset:192
	s_add_u32 s98, s36, 0x70000
	s_addc_u32 s99, s37, 0
	global_load_dwordx4 v[188:191], v201, s[98:99] offset:64
	s_waitcnt vmcnt(10)
	v_pk_mul_f32 v[168:169], v[168:169], s[52:53] op_sel_hi:[1,0]
	v_pk_mul_f32 v[170:171], v[170:171], s[52:53] op_sel_hi:[1,0]
	v_pk_fma_f32 v[128:129], v[92:93], v[128:129], v[168:169]
	v_pk_fma_f32 v[130:131], v[94:95], v[130:131], v[170:171]
	s_add_u32 s100, s36, 0x60000
	s_addc_u32 s101, s37, 0
	global_store_dwordx4 v201, v[128:131], s[100:101]
	s_add_u32 s98, s36, 0x70000
	s_addc_u32 s99, s37, 0
	global_load_dwordx4 v[168:171], v201, s[98:99] offset:128
	s_waitcnt vmcnt(10)
	v_pk_mul_f32 v[172:173], v[172:173], s[52:53] op_sel_hi:[1,0]
	v_pk_mul_f32 v[174:175], v[174:175], s[52:53] op_sel_hi:[1,0]
	v_pk_fma_f32 v[100:101], v[132:133], v[100:101], v[172:173]
	v_pk_fma_f32 v[102:103], v[134:135], v[102:103], v[174:175]
	s_add_u32 s100, s36, 0x60000
	s_addc_u32 s101, s37, 0
	global_store_dwordx4 v201, v[100:103], s[100:101] offset:64
	s_add_u32 s98, s36, 0x70000
	s_addc_u32 s99, s37, 0
	global_load_dwordx4 v[172:175], v201, s[98:99] offset:192
	s_waitcnt vmcnt(10)
	v_pk_mul_f32 v[176:177], v[176:177], s[52:53] op_sel_hi:[1,0]
	v_pk_mul_f32 v[178:179], v[178:179], s[52:53] op_sel_hi:[1,0]
	v_pk_fma_f32 v[64:65], v[136:137], v[64:65], v[176:177]
	v_pk_fma_f32 v[66:67], v[138:139], v[66:67], v[178:179]
	s_add_u32 s100, s36, 0x60000
	s_addc_u32 s101, s37, 0
	global_store_dwordx4 v201, v[64:67], s[100:101] offset:128
	s_waitcnt vmcnt(9)
	v_pk_mul_f32 v[180:181], v[180:181], s[52:53] op_sel_hi:[1,0]
	v_pk_mul_f32 v[182:183], v[182:183], s[52:53] op_sel_hi:[1,0]
	v_pk_fma_f32 v[32:33], v[164:165], v[32:33], v[180:181]
	v_pk_fma_f32 v[34:35], v[166:167], v[34:35], v[182:183]
	s_add_u32 s100, s36, 0x60000
	s_addc_u32 s101, s37, 0
	global_store_dwordx4 v201, v[32:35], s[100:101] offset:192
	s_waitcnt vmcnt(8)
	v_pk_mul_f32 v[184:185], v[184:185], s[52:53] op_sel_hi:[1,0]
	v_pk_mul_f32 v[186:187], v[186:187], s[52:53] op_sel_hi:[1,0]
	v_pk_fma_f32 v[124:125], v[92:93], v[124:125], v[184:185]
	v_pk_fma_f32 v[126:127], v[94:95], v[126:127], v[186:187]
	s_add_u32 s100, s36, 0x70000
	s_addc_u32 s101, s37, 0
	global_store_dwordx4 v201, v[124:127], s[100:101]
	s_waitcnt vmcnt(7)
	v_pk_mul_f32 v[188:189], v[188:189], s[52:53] op_sel_hi:[1,0]
	v_pk_mul_f32 v[190:191], v[190:191], s[52:53] op_sel_hi:[1,0]
	v_pk_fma_f32 v[88:89], v[132:133], v[88:89], v[188:189]
	v_pk_fma_f32 v[90:91], v[134:135], v[90:91], v[190:191]
	s_add_u32 s100, s36, 0x70000
	s_addc_u32 s101, s37, 0
	global_store_dwordx4 v201, v[88:91], s[100:101] offset:64
	s_waitcnt vmcnt(6)
	v_pk_mul_f32 v[168:169], v[168:169], s[52:53] op_sel_hi:[1,0]
	v_pk_mul_f32 v[170:171], v[170:171], s[52:53] op_sel_hi:[1,0]
	v_pk_fma_f32 v[56:57], v[136:137], v[56:57], v[168:169]
	v_pk_fma_f32 v[58:59], v[138:139], v[58:59], v[170:171]
	s_add_u32 s100, s36, 0x70000
	s_addc_u32 s101, s37, 0
	global_store_dwordx4 v201, v[56:59], s[100:101] offset:128
	s_waitcnt vmcnt(5)
	v_pk_mul_f32 v[172:173], v[172:173], s[52:53] op_sel_hi:[1,0]
	v_pk_mul_f32 v[174:175], v[174:175], s[52:53] op_sel_hi:[1,0]
	v_pk_fma_f32 v[24:25], v[164:165], v[24:25], v[172:173]
	v_pk_fma_f32 v[26:27], v[166:167], v[26:27], v[174:175]
	s_add_u32 s100, s36, 0x70000
	s_addc_u32 s101, s37, 0
	global_store_dwordx4 v201, v[24:27], s[100:101] offset:192
	s_branch .LBB0_1054
